# previous + LDS fragment reads software-pipelined inside the compiler's 128x128 MFMA blocks (merge x4, out<2>, ffn2<2>), counted lgkmcnt waits
# speedup vs baseline: 1.0704x; 1.0036x over previous
; #define GLOAD(RA, RB, kt_) _Pragma("unroll") for (int i = 0; i < 4; ++i) { \
;     RA[i] = *(const u32x4*)(Ap + (size_t)(32 * i) * lda + (kt_) * 64); \
;     RB[i] = *(const u32x4*)(Bp + (size_t)(32 * i) * ldb + (kt_) * 64); }
; #define LSTORE(RA, RB, buf_) _Pragma("unroll") for (int i = 0; i < 4; ++i) { \
;     *(u32x4*)(smem + (buf_) * 16384 + woff + i * 4096) = RA[i]; \
;     *(u32x4*)(smem + 32768 + (buf_) * 16384 + woff + i * 4096) = RB[i]; }
; DI void gemm_kloop(f32x16 (&acc)[2][2], const u16* __restrict__ A, int lda, const u16* __restrict__ B, int ldb, int K,
;                    char* smem) {
;     ...
;   const int woff = lr * 128 + ((lc ^ ((lr >> 1) & 7)) << 4);
;   const int sw = (r >> 1) & 7;
;   const int aoff = (wr * 64 + r) * 128, boff = 32768 + (wc * 64 + r) * 128;
;   GLOAD(ra0, rb0, 0)
;   GLOAD(ra1, rb1, 1)
;   __syncthreads();
;   LSTORE(ra0, rb0, 0)
;   __syncthreads();
; #pragma unroll 1
;   for (int kt = 0; kt < nk; kt += 2) {
;     if (kt + 2 < nk) GLOAD(ra0, rb0, kt + 2)
;     COMPUTE(0)
;     LSTORE(ra1, rb1, 1)
;     __syncthreads();
;     if (kt + 3 < nk) GLOAD(ra1, rb1, kt + 3)
;     COMPUTE(1)
;     if (kt + 2 < nk) LSTORE(ra0, rb0, 0)
;     __syncthreads();
.LBB0_52:
	s_setprio 1
	v_add_u32_e32 v145, v140, v141
	v_add_u32_e32 v149, v138, v141
	v_add_u32_e32 v146, v140, v142
	v_add_u32_e32 v147, v140, v143
	v_add_u32_e32 v148, v140, v144
	v_add_u32_e32 v150, v138, v142
	v_add_u32_e32 v151, v138, v143
	v_add_u32_e32 v152, v138, v144
	ds_read_b128 v[208:211], v145
	ds_read_b128 v[212:215], v149 offset:32768
	ds_read_b128 v[216:219], v149 offset:36864
	ds_read_b128 v[220:223], v145 offset:4096
	ds_read_b128 v[224:227], v146
	ds_read_b128 v[228:231], v150 offset:32768
	ds_read_b128 v[232:235], v150 offset:36864
	ds_read_b128 v[236:239], v146 offset:4096
	s_waitcnt lgkmcnt(6)
	v_mfma_f32_32x32x16_bf16 v[50:65], v[208:211], v[212:215], v[50:65]
	s_waitcnt lgkmcnt(5)
	v_mfma_f32_32x32x16_bf16 v[34:49], v[208:211], v[216:219], v[34:49]
	ds_read_b128 v[208:211], v151 offset:32768
	s_waitcnt lgkmcnt(5)
	v_mfma_f32_32x32x16_bf16 v[18:33], v[220:223], v[212:215], v[18:33]
	ds_read_b128 v[212:215], v147
	s_waitcnt lgkmcnt(6)
	v_mfma_f32_32x32x16_bf16 v[2:17], v[220:223], v[216:219], v[2:17]
	ds_read_b128 v[220:223], v151 offset:36864
	ds_read_b128 v[216:219], v147 offset:4096
	s_waitcnt lgkmcnt(6)
	v_mfma_f32_32x32x16_bf16 v[50:65], v[224:227], v[228:231], v[50:65]
	s_waitcnt lgkmcnt(5)
	v_mfma_f32_32x32x16_bf16 v[34:49], v[224:227], v[232:235], v[34:49]
	ds_read_b128 v[224:227], v148
	s_waitcnt lgkmcnt(5)
	v_mfma_f32_32x32x16_bf16 v[18:33], v[236:239], v[228:231], v[18:33]
	ds_read_b128 v[228:231], v152 offset:32768
	s_waitcnt lgkmcnt(6)
	v_mfma_f32_32x32x16_bf16 v[2:17], v[236:239], v[232:235], v[2:17]
	ds_read_b128 v[236:239], v152 offset:36864
	ds_read_b128 v[232:235], v148 offset:4096
	s_waitcnt lgkmcnt(6)
	v_mfma_f32_32x32x16_bf16 v[50:65], v[212:215], v[208:211], v[50:65]
	s_waitcnt lgkmcnt(5)
	v_mfma_f32_32x32x16_bf16 v[34:49], v[212:215], v[220:223], v[34:49]
	s_waitcnt lgkmcnt(4)
	v_mfma_f32_32x32x16_bf16 v[18:33], v[216:219], v[208:211], v[18:33]
	s_waitcnt lgkmcnt(4)
	v_mfma_f32_32x32x16_bf16 v[2:17], v[216:219], v[220:223], v[2:17]
	s_waitcnt lgkmcnt(2)
	v_mfma_f32_32x32x16_bf16 v[50:65], v[224:227], v[228:231], v[50:65]
	s_waitcnt lgkmcnt(1)
	v_mfma_f32_32x32x16_bf16 v[34:49], v[224:227], v[236:239], v[34:49]
	s_waitcnt lgkmcnt(0)
	v_mfma_f32_32x32x16_bf16 v[18:33], v[232:235], v[228:231], v[18:33]
	s_waitcnt lgkmcnt(0)
	v_mfma_f32_32x32x16_bf16 v[2:17], v[232:235], v[236:239], v[2:17]
	s_setprio 0
	s_cmp_gt_u32 s42, 40
	s_waitcnt vmcnt(7)
	ds_write_b128 v139, v[90:93] offset:16384
	s_waitcnt vmcnt(3)
	ds_write_b128 v139, v[98:101] offset:49152
	ds_write_b128 v139, v[102:105] offset:20480
	s_waitcnt vmcnt(2)
	ds_write_b128 v139, v[106:109] offset:53248
	ds_write_b128 v139, v[110:113] offset:24576
	s_waitcnt vmcnt(1)
	ds_write_b128 v139, v[114:117] offset:57344
	ds_write_b128 v139, v[122:125] offset:28672
	s_waitcnt vmcnt(0)
	ds_write_b128 v139, v[126:129] offset:61440
	s_waitcnt lgkmcnt(0)
	s_barrier
	s_cbranch_scc1 .LBB0_54
	v_add_co_u32_e32 v90, vcc, 0xb360000, v136
	s_nop 1
	v_addc_co_u32_e32 v91, vcc, 0, v137, vcc
	v_add_co_u32_e32 v98, vcc, 0x1dc0000, v134
	global_load_dwordx4 v[90:93], v[90:91], off offset:384
	s_nop 0
	v_addc_co_u32_e32 v99, vcc, 0, v135, vcc
	v_add_co_u32_e32 v102, vcc, 0xb38c000, v136
	global_load_dwordx4 v[98:101], v[98:99], off offset:384
	s_nop 0
	v_addc_co_u32_e32 v103, vcc, 0, v137, vcc
	v_add_co_u32_e32 v106, vcc, 0x1dec000, v134
	global_load_dwordx4 v[102:105], v[102:103], off offset:384
	s_nop 0
	v_addc_co_u32_e32 v107, vcc, 0, v135, vcc
	v_add_co_u32_e32 v110, vcc, 0xb3b8000, v136
	global_load_dwordx4 v[106:109], v[106:107], off offset:384
	s_nop 0
	v_addc_co_u32_e32 v111, vcc, 0, v137, vcc
	v_add_co_u32_e32 v114, vcc, 0x1e18000, v134
	global_load_dwordx4 v[110:113], v[110:111], off offset:384
	s_nop 0
	v_addc_co_u32_e32 v115, vcc, 0, v135, vcc
	v_add_co_u32_e32 v122, vcc, 0xb3e4000, v136
	global_load_dwordx4 v[114:117], v[114:115], off offset:384
	s_nop 0
	v_addc_co_u32_e32 v123, vcc, 0, v137, vcc
	v_add_co_u32_e32 v126, vcc, 0x1e44000, v134
	global_load_dwordx4 v[122:125], v[122:123], off offset:384
	s_nop 0
	v_addc_co_u32_e32 v127, vcc, 0, v135, vcc
	global_load_dwordx4 v[126:129], v[126:127], off offset:384
.LBB0_54:
	s_setprio 1
	ds_read_b128 v[208:211], v145 offset:16384
	ds_read_b128 v[212:215], v149 offset:49152
	ds_read_b128 v[216:219], v149 offset:53248
	ds_read_b128 v[220:223], v145 offset:20480
	ds_read_b128 v[224:227], v146 offset:16384
	ds_read_b128 v[228:231], v150 offset:49152
	ds_read_b128 v[232:235], v150 offset:53248
	ds_read_b128 v[236:239], v146 offset:20480
	s_waitcnt lgkmcnt(6)
	v_mfma_f32_32x32x16_bf16 v[50:65], v[208:211], v[212:215], v[50:65]
	s_waitcnt lgkmcnt(5)
	v_mfma_f32_32x32x16_bf16 v[34:49], v[208:211], v[216:219], v[34:49]
	ds_read_b128 v[208:211], v147 offset:16384
	s_waitcnt lgkmcnt(5)
	v_mfma_f32_32x32x16_bf16 v[18:33], v[220:223], v[212:215], v[18:33]
	ds_read_b128 v[212:215], v151 offset:49152
	s_waitcnt lgkmcnt(6)
	v_mfma_f32_32x32x16_bf16 v[2:17], v[220:223], v[216:219], v[2:17]
	ds_read_b128 v[220:223], v151 offset:53248
	ds_read_b128 v[216:219], v147 offset:20480
	s_waitcnt lgkmcnt(6)
	v_mfma_f32_32x32x16_bf16 v[50:65], v[224:227], v[228:231], v[50:65]
	s_waitcnt lgkmcnt(5)
	v_mfma_f32_32x32x16_bf16 v[34:49], v[224:227], v[232:235], v[34:49]
	ds_read_b128 v[224:227], v148 offset:16384
	s_waitcnt lgkmcnt(5)
	v_mfma_f32_32x32x16_bf16 v[18:33], v[236:239], v[228:231], v[18:33]
	ds_read_b128 v[228:231], v152 offset:49152
	s_waitcnt lgkmcnt(6)
	v_mfma_f32_32x32x16_bf16 v[2:17], v[236:239], v[232:235], v[2:17]
	ds_read_b128 v[236:239], v152 offset:53248
	ds_read_b128 v[232:235], v148 offset:20480
	s_waitcnt lgkmcnt(6)
	v_mfma_f32_32x32x16_bf16 v[50:65], v[208:211], v[212:215], v[50:65]
	s_waitcnt lgkmcnt(5)
	v_mfma_f32_32x32x16_bf16 v[34:49], v[208:211], v[220:223], v[34:49]
	s_waitcnt lgkmcnt(4)
	v_mfma_f32_32x32x16_bf16 v[18:33], v[216:219], v[212:215], v[18:33]
	s_waitcnt lgkmcnt(4)
	v_mfma_f32_32x32x16_bf16 v[2:17], v[216:219], v[220:223], v[2:17]
	s_waitcnt lgkmcnt(2)
	v_mfma_f32_32x32x16_bf16 v[50:65], v[224:227], v[228:231], v[50:65]
	s_waitcnt lgkmcnt(1)
	v_mfma_f32_32x32x16_bf16 v[34:49], v[224:227], v[236:239], v[34:49]
	s_waitcnt lgkmcnt(0)
	v_mfma_f32_32x32x16_bf16 v[18:33], v[232:235], v[228:231], v[18:33]
	s_waitcnt lgkmcnt(0)
	v_mfma_f32_32x32x16_bf16 v[2:17], v[232:235], v[236:239], v[2:17]
	s_setprio 0
	s_andn2_b64 vcc, exec, s[28:29]
	s_cbranch_vccnz .LBB0_49
	ds_write_b128 v139, v[66:69]
	ds_write_b128 v139, v[70:73] offset:32768
	ds_write_b128 v139, v[74:77] offset:4096
	ds_write_b128 v139, v[78:81] offset:36864
	ds_write_b128 v139, v[82:85] offset:8192
	ds_write_b128 v139, v[86:89] offset:40960
	ds_write_b128 v139, v[94:97] offset:12288
	ds_write_b128 v139, v[118:121] offset:45056
	s_branch .LBB0_49

; #define GLOAD(RA, RB, kt_) _Pragma("unroll") for (int i = 0; i < 4; ++i) { \
;     RA[i] = *(const u32x4*)(Ap + (size_t)(32 * i) * lda + (kt_) * 64); \
;     RB[i] = *(const u32x4*)(Bp + (size_t)(32 * i) * ldb + (kt_) * 64); }
; #define LSTORE(RA, RB, buf_) _Pragma("unroll") for (int i = 0; i < 4; ++i) { \
;     *(u32x4*)(smem + (buf_) * 16384 + woff + i * 4096) = RA[i]; \
;     *(u32x4*)(smem + 32768 + (buf_) * 16384 + woff + i * 4096) = RB[i]; }
; DI void gemm_kloop(f32x16 (&acc)[2][2], const u16* __restrict__ A, int lda, const u16* __restrict__ B, int ldb, int K,
;                    char* smem) {
;     ...
;   const int woff = lr * 128 + ((lc ^ ((lr >> 1) & 7)) << 4);
;   const int sw = (r >> 1) & 7;
;   const int aoff = (wr * 64 + r) * 128, boff = 32768 + (wc * 64 + r) * 128;
;   GLOAD(ra0, rb0, 0)
;   GLOAD(ra1, rb1, 1)
;   __syncthreads();
;   LSTORE(ra0, rb0, 0)
;   __syncthreads();
; #pragma unroll 1
;   for (int kt = 0; kt < nk; kt += 2) {
;     if (kt + 2 < nk) GLOAD(ra0, rb0, kt + 2)
;     COMPUTE(0)
;     LSTORE(ra1, rb1, 1)
;     __syncthreads();
;     if (kt + 3 < nk) GLOAD(ra1, rb1, kt + 3)
;     COMPUTE(1)
;     if (kt + 2 < nk) LSTORE(ra0, rb0, 0)
;     __syncthreads();
.LBB0_98:
	s_setprio 1
	v_add_u32_e32 v145, v140, v141
	v_add_u32_e32 v149, v138, v141
	v_add_u32_e32 v146, v140, v142
	v_add_u32_e32 v147, v140, v143
	v_add_u32_e32 v148, v140, v144
	v_add_u32_e32 v150, v138, v142
	v_add_u32_e32 v151, v138, v143
	v_add_u32_e32 v152, v138, v144
	ds_read_b128 v[208:211], v145
	ds_read_b128 v[212:215], v149 offset:32768
	ds_read_b128 v[216:219], v149 offset:36864
	ds_read_b128 v[220:223], v145 offset:4096
	ds_read_b128 v[224:227], v146
	ds_read_b128 v[228:231], v150 offset:32768
	ds_read_b128 v[232:235], v150 offset:36864
	ds_read_b128 v[236:239], v146 offset:4096
	s_waitcnt lgkmcnt(6)
	v_mfma_f32_32x32x16_bf16 v[50:65], v[208:211], v[212:215], v[50:65]
	s_waitcnt lgkmcnt(5)
	v_mfma_f32_32x32x16_bf16 v[34:49], v[208:211], v[216:219], v[34:49]
	ds_read_b128 v[208:211], v151 offset:32768
	s_waitcnt lgkmcnt(5)
	v_mfma_f32_32x32x16_bf16 v[18:33], v[220:223], v[212:215], v[18:33]
	ds_read_b128 v[212:215], v147
	s_waitcnt lgkmcnt(6)
	v_mfma_f32_32x32x16_bf16 v[2:17], v[220:223], v[216:219], v[2:17]
	ds_read_b128 v[220:223], v151 offset:36864
	ds_read_b128 v[216:219], v147 offset:4096
	s_waitcnt lgkmcnt(6)
	v_mfma_f32_32x32x16_bf16 v[50:65], v[224:227], v[228:231], v[50:65]
	s_waitcnt lgkmcnt(5)
	v_mfma_f32_32x32x16_bf16 v[34:49], v[224:227], v[232:235], v[34:49]
	ds_read_b128 v[224:227], v148
	s_waitcnt lgkmcnt(5)
	v_mfma_f32_32x32x16_bf16 v[18:33], v[236:239], v[228:231], v[18:33]
	ds_read_b128 v[228:231], v152 offset:32768
	s_waitcnt lgkmcnt(6)
	v_mfma_f32_32x32x16_bf16 v[2:17], v[236:239], v[232:235], v[2:17]
	ds_read_b128 v[236:239], v152 offset:36864
	ds_read_b128 v[232:235], v148 offset:4096
	s_waitcnt lgkmcnt(6)
	v_mfma_f32_32x32x16_bf16 v[50:65], v[212:215], v[208:211], v[50:65]
	s_waitcnt lgkmcnt(5)
	v_mfma_f32_32x32x16_bf16 v[34:49], v[212:215], v[220:223], v[34:49]
	s_waitcnt lgkmcnt(4)
	v_mfma_f32_32x32x16_bf16 v[18:33], v[216:219], v[208:211], v[18:33]
	s_waitcnt lgkmcnt(4)
	v_mfma_f32_32x32x16_bf16 v[2:17], v[216:219], v[220:223], v[2:17]
	s_waitcnt lgkmcnt(2)
	v_mfma_f32_32x32x16_bf16 v[50:65], v[224:227], v[228:231], v[50:65]
	s_waitcnt lgkmcnt(1)
	v_mfma_f32_32x32x16_bf16 v[34:49], v[224:227], v[236:239], v[34:49]
	s_waitcnt lgkmcnt(0)
	v_mfma_f32_32x32x16_bf16 v[18:33], v[232:235], v[228:231], v[18:33]
	s_waitcnt lgkmcnt(0)
	v_mfma_f32_32x32x16_bf16 v[2:17], v[232:235], v[236:239], v[2:17]
	s_setprio 0
	s_cmp_gt_u32 s1, 12
	s_waitcnt vmcnt(7)
	ds_write_b128 v139, v[90:93] offset:16384
	s_waitcnt vmcnt(3)
	ds_write_b128 v139, v[98:101] offset:49152
	ds_write_b128 v139, v[102:105] offset:20480
	s_waitcnt vmcnt(2)
	ds_write_b128 v139, v[106:109] offset:53248
	ds_write_b128 v139, v[110:113] offset:24576
	s_waitcnt vmcnt(1)
	ds_write_b128 v139, v[114:117] offset:57344
	ds_write_b128 v139, v[122:125] offset:28672
	s_waitcnt vmcnt(0)
	ds_write_b128 v139, v[126:129] offset:61440
	s_waitcnt lgkmcnt(0)
	s_barrier
	s_cbranch_scc1 .LBB0_100
	v_add_co_u32_e32 v90, vcc, 0x6b60000, v136
	s_nop 1
	v_addc_co_u32_e32 v91, vcc, 0, v137, vcc
	v_add_co_u32_e32 v98, vcc, 0x10c0000, v134
	global_load_dwordx4 v[90:93], v[90:91], off offset:384
	s_nop 0
	v_addc_co_u32_e32 v99, vcc, 0, v135, vcc
	v_add_co_u32_e32 v102, vcc, 0x6b70000, v136
	global_load_dwordx4 v[98:101], v[98:99], off offset:384
	s_nop 0
	v_addc_co_u32_e32 v103, vcc, 0, v137, vcc
	v_add_co_u32_e32 v106, vcc, 0x10d0000, v134
	global_load_dwordx4 v[102:105], v[102:103], off offset:384
	s_nop 0
	v_addc_co_u32_e32 v107, vcc, 0, v135, vcc
	v_add_co_u32_e32 v110, vcc, 0x6b80000, v136
	global_load_dwordx4 v[106:109], v[106:107], off offset:384
	s_nop 0
	v_addc_co_u32_e32 v111, vcc, 0, v137, vcc
	v_add_co_u32_e32 v114, vcc, 0x10e0000, v134
	global_load_dwordx4 v[110:113], v[110:111], off offset:384
	s_nop 0
	v_addc_co_u32_e32 v115, vcc, 0, v135, vcc
	v_add_co_u32_e32 v122, vcc, 0x6b90000, v136
	global_load_dwordx4 v[114:117], v[114:115], off offset:384
	s_nop 0
	v_addc_co_u32_e32 v123, vcc, 0, v137, vcc
	v_add_co_u32_e32 v126, vcc, 0x10f0000, v134
	global_load_dwordx4 v[122:125], v[122:123], off offset:384
	s_nop 0
	v_addc_co_u32_e32 v127, vcc, 0, v135, vcc
	global_load_dwordx4 v[126:129], v[126:127], off offset:384
.LBB0_100:
	s_setprio 1
	ds_read_b128 v[208:211], v145 offset:16384
	ds_read_b128 v[212:215], v149 offset:49152
	ds_read_b128 v[216:219], v149 offset:53248
	ds_read_b128 v[220:223], v145 offset:20480
	ds_read_b128 v[224:227], v146 offset:16384
	ds_read_b128 v[228:231], v150 offset:49152
	ds_read_b128 v[232:235], v150 offset:53248
	ds_read_b128 v[236:239], v146 offset:20480
	s_waitcnt lgkmcnt(6)
	v_mfma_f32_32x32x16_bf16 v[50:65], v[208:211], v[212:215], v[50:65]
	s_waitcnt lgkmcnt(5)
	v_mfma_f32_32x32x16_bf16 v[34:49], v[208:211], v[216:219], v[34:49]
	ds_read_b128 v[208:211], v147 offset:16384
	s_waitcnt lgkmcnt(5)
	v_mfma_f32_32x32x16_bf16 v[18:33], v[220:223], v[212:215], v[18:33]
	ds_read_b128 v[212:215], v151 offset:49152
	s_waitcnt lgkmcnt(6)
	v_mfma_f32_32x32x16_bf16 v[2:17], v[220:223], v[216:219], v[2:17]
	ds_read_b128 v[220:223], v151 offset:53248
	ds_read_b128 v[216:219], v147 offset:20480
	s_waitcnt lgkmcnt(6)
	v_mfma_f32_32x32x16_bf16 v[50:65], v[224:227], v[228:231], v[50:65]
	s_waitcnt lgkmcnt(5)
	v_mfma_f32_32x32x16_bf16 v[34:49], v[224:227], v[232:235], v[34:49]
	ds_read_b128 v[224:227], v148 offset:16384
	s_waitcnt lgkmcnt(5)
	v_mfma_f32_32x32x16_bf16 v[18:33], v[236:239], v[228:231], v[18:33]
	ds_read_b128 v[228:231], v152 offset:49152
	s_waitcnt lgkmcnt(6)
	v_mfma_f32_32x32x16_bf16 v[2:17], v[236:239], v[232:235], v[2:17]
	ds_read_b128 v[236:239], v152 offset:53248
	ds_read_b128 v[232:235], v148 offset:20480
	s_waitcnt lgkmcnt(6)
	v_mfma_f32_32x32x16_bf16 v[50:65], v[208:211], v[212:215], v[50:65]
	s_waitcnt lgkmcnt(5)
	v_mfma_f32_32x32x16_bf16 v[34:49], v[208:211], v[220:223], v[34:49]
	s_waitcnt lgkmcnt(4)
	v_mfma_f32_32x32x16_bf16 v[18:33], v[216:219], v[212:215], v[18:33]
	s_waitcnt lgkmcnt(4)
	v_mfma_f32_32x32x16_bf16 v[2:17], v[216:219], v[220:223], v[2:17]
	s_waitcnt lgkmcnt(2)
	v_mfma_f32_32x32x16_bf16 v[50:65], v[224:227], v[228:231], v[50:65]
	s_waitcnt lgkmcnt(1)
	v_mfma_f32_32x32x16_bf16 v[34:49], v[224:227], v[236:239], v[34:49]
	s_waitcnt lgkmcnt(0)
	v_mfma_f32_32x32x16_bf16 v[18:33], v[232:235], v[228:231], v[18:33]
	s_waitcnt lgkmcnt(0)
	v_mfma_f32_32x32x16_bf16 v[2:17], v[232:235], v[236:239], v[2:17]
	s_setprio 0
	s_andn2_b64 vcc, exec, s[38:39]
	s_cbranch_vccnz .LBB0_95
	ds_write_b128 v139, v[66:69]
	ds_write_b128 v139, v[70:73] offset:32768
	ds_write_b128 v139, v[74:77] offset:4096
	ds_write_b128 v139, v[78:81] offset:36864
	ds_write_b128 v139, v[82:85] offset:8192
	ds_write_b128 v139, v[86:89] offset:40960
	ds_write_b128 v139, v[94:97] offset:12288
	ds_write_b128 v139, v[118:121] offset:45056
	s_branch .LBB0_95

; #define GLOAD(RA, RB, kt_) _Pragma("unroll") for (int i = 0; i < 4; ++i) { \
;     RA[i] = *(const u32x4*)(Ap + (size_t)(32 * i) * lda + (kt_) * 64); \
;     RB[i] = *(const u32x4*)(Bp + (size_t)(32 * i) * ldb + (kt_) * 64); }
; #define LSTORE(RA, RB, buf_) _Pragma("unroll") for (int i = 0; i < 4; ++i) { \
;     *(u32x4*)(smem + (buf_) * 16384 + woff + i * 4096) = RA[i]; \
;     *(u32x4*)(smem + 32768 + (buf_) * 16384 + woff + i * 4096) = RB[i]; }
; DI void gemm_kloop(f32x16 (&acc)[2][2], const u16* __restrict__ A, int lda, const u16* __restrict__ B, int ldb, int K,
;                    char* smem) {
;     ...
;   const int woff = lr * 128 + ((lc ^ ((lr >> 1) & 7)) << 4);
;   const int sw = (r >> 1) & 7;
;   const int aoff = (wr * 64 + r) * 128, boff = 32768 + (wc * 64 + r) * 128;
;   GLOAD(ra0, rb0, 0)
;   GLOAD(ra1, rb1, 1)
;   __syncthreads();
;   LSTORE(ra0, rb0, 0)
;   __syncthreads();
; #pragma unroll 1
;   for (int kt = 0; kt < nk; kt += 2) {
;     if (kt + 2 < nk) GLOAD(ra0, rb0, kt + 2)
;     COMPUTE(0)
;     LSTORE(ra1, rb1, 1)
;     __syncthreads();
;     if (kt + 3 < nk) GLOAD(ra1, rb1, kt + 3)
;     COMPUTE(1)
;     if (kt + 2 < nk) LSTORE(ra0, rb0, 0)
;     __syncthreads();
; DI void gemm_merge_phase(const Params& p, int mrows, int bid, int nb, char* smem) {
;     ...
;     gemm_kloop(a, H + (size_t)row0 * 1024, 1024, WT + WT_IN + (size_t)(NIN + col0) * 1024, 1024, 1024, smem);
.LBB0_112:
	s_setprio 1
	v_add_u32_e32 v145, v140, v141
	v_add_u32_e32 v149, v139, v141
	v_add_u32_e32 v146, v140, v142
	v_add_u32_e32 v147, v140, v143
	v_add_u32_e32 v148, v140, v144
	v_add_u32_e32 v150, v139, v142
	v_add_u32_e32 v151, v139, v143
	v_add_u32_e32 v152, v139, v144
	ds_read_b128 v[208:211], v145
	ds_read_b128 v[212:215], v149 offset:32768
	ds_read_b128 v[216:219], v149 offset:36864
	ds_read_b128 v[220:223], v145 offset:4096
	ds_read_b128 v[224:227], v146
	ds_read_b128 v[228:231], v150 offset:32768
	ds_read_b128 v[232:235], v150 offset:36864
	ds_read_b128 v[236:239], v146 offset:4096
	s_waitcnt lgkmcnt(6)
	v_mfma_f32_32x32x16_bf16 v[50:65], v[208:211], v[212:215], v[50:65]
	s_waitcnt lgkmcnt(5)
	v_mfma_f32_32x32x16_bf16 v[34:49], v[208:211], v[216:219], v[34:49]
	ds_read_b128 v[208:211], v151 offset:32768
	s_waitcnt lgkmcnt(5)
	v_mfma_f32_32x32x16_bf16 v[18:33], v[220:223], v[212:215], v[18:33]
	ds_read_b128 v[212:215], v147
	s_waitcnt lgkmcnt(6)
	v_mfma_f32_32x32x16_bf16 v[2:17], v[220:223], v[216:219], v[2:17]
	ds_read_b128 v[220:223], v151 offset:36864
	ds_read_b128 v[216:219], v147 offset:4096
	s_waitcnt lgkmcnt(6)
	v_mfma_f32_32x32x16_bf16 v[50:65], v[224:227], v[228:231], v[50:65]
	s_waitcnt lgkmcnt(5)
	v_mfma_f32_32x32x16_bf16 v[34:49], v[224:227], v[232:235], v[34:49]
	ds_read_b128 v[224:227], v148
	s_waitcnt lgkmcnt(5)
	v_mfma_f32_32x32x16_bf16 v[18:33], v[236:239], v[228:231], v[18:33]
	ds_read_b128 v[228:231], v152 offset:32768
	s_waitcnt lgkmcnt(6)
	v_mfma_f32_32x32x16_bf16 v[2:17], v[236:239], v[232:235], v[2:17]
	ds_read_b128 v[236:239], v152 offset:36864
	ds_read_b128 v[232:235], v148 offset:4096
	s_waitcnt lgkmcnt(6)
	v_mfma_f32_32x32x16_bf16 v[50:65], v[212:215], v[208:211], v[50:65]
	s_waitcnt lgkmcnt(5)
	v_mfma_f32_32x32x16_bf16 v[34:49], v[212:215], v[220:223], v[34:49]
	s_waitcnt lgkmcnt(4)
	v_mfma_f32_32x32x16_bf16 v[18:33], v[216:219], v[208:211], v[18:33]
	s_waitcnt lgkmcnt(4)
	v_mfma_f32_32x32x16_bf16 v[2:17], v[216:219], v[220:223], v[2:17]
	s_waitcnt lgkmcnt(2)
	v_mfma_f32_32x32x16_bf16 v[50:65], v[224:227], v[228:231], v[50:65]
	s_waitcnt lgkmcnt(1)
	v_mfma_f32_32x32x16_bf16 v[34:49], v[224:227], v[236:239], v[34:49]
	s_waitcnt lgkmcnt(0)
	v_mfma_f32_32x32x16_bf16 v[18:33], v[232:235], v[228:231], v[18:33]
	s_waitcnt lgkmcnt(0)
	v_mfma_f32_32x32x16_bf16 v[2:17], v[232:235], v[236:239], v[2:17]
	s_setprio 0
	s_cmp_gt_u32 s29, 12
	s_waitcnt vmcnt(7)
	ds_write_b128 v138, v[82:85] offset:16384
	s_waitcnt vmcnt(3)
	ds_write_b128 v138, v[90:93] offset:49152
	ds_write_b128 v138, v[98:101] offset:20480
	s_waitcnt vmcnt(2)
	ds_write_b128 v138, v[106:109] offset:53248
	ds_write_b128 v138, v[110:113] offset:24576
	s_waitcnt vmcnt(1)
	ds_write_b128 v138, v[114:117] offset:57344
	ds_write_b128 v138, v[118:121] offset:28672
	s_waitcnt vmcnt(0)
	ds_write_b128 v138, v[122:125] offset:61440
	s_waitcnt lgkmcnt(0)
	s_barrier
	s_cbranch_scc1 .LBB0_114
	v_add_co_u32_e32 v82, vcc, 0x2360000, v136
	s_nop 1
	v_addc_co_u32_e32 v83, vcc, 0, v137, vcc
	v_add_co_u32_e32 v90, vcc, 0x9c0000, v134
	global_load_dwordx4 v[82:85], v[82:83], off offset:384
	s_nop 0
	v_addc_co_u32_e32 v91, vcc, 0, v135, vcc
	v_add_co_u32_e32 v98, vcc, 0x2370000, v136
	global_load_dwordx4 v[90:93], v[90:91], off offset:384
	s_nop 0
	v_addc_co_u32_e32 v99, vcc, 0, v137, vcc
	v_add_co_u32_e32 v106, vcc, 0x9d0000, v134
	global_load_dwordx4 v[98:101], v[98:99], off offset:384
	s_nop 0
	v_addc_co_u32_e32 v107, vcc, 0, v135, vcc
	v_add_co_u32_e32 v110, vcc, 0x2380000, v136
	global_load_dwordx4 v[106:109], v[106:107], off offset:384
	s_nop 0
	v_addc_co_u32_e32 v111, vcc, 0, v137, vcc
	v_add_co_u32_e32 v114, vcc, 0x9e0000, v134
	global_load_dwordx4 v[110:113], v[110:111], off offset:384
	s_nop 0
	v_addc_co_u32_e32 v115, vcc, 0, v135, vcc
	v_add_co_u32_e32 v118, vcc, 0x2390000, v136
	global_load_dwordx4 v[114:117], v[114:115], off offset:384
	s_nop 0
	v_addc_co_u32_e32 v119, vcc, 0, v137, vcc
	v_add_co_u32_e32 v122, vcc, 0x9f0000, v134
	global_load_dwordx4 v[118:121], v[118:119], off offset:384
	s_nop 0
	v_addc_co_u32_e32 v123, vcc, 0, v135, vcc
	global_load_dwordx4 v[122:125], v[122:123], off offset:384
.LBB0_114:
	s_setprio 1
	ds_read_b128 v[208:211], v145 offset:16384
	ds_read_b128 v[212:215], v149 offset:49152
	ds_read_b128 v[216:219], v149 offset:53248
	ds_read_b128 v[220:223], v145 offset:20480
	ds_read_b128 v[224:227], v146 offset:16384
	ds_read_b128 v[228:231], v150 offset:49152
	ds_read_b128 v[232:235], v150 offset:53248
	ds_read_b128 v[236:239], v146 offset:20480
	s_waitcnt lgkmcnt(6)
	v_mfma_f32_32x32x16_bf16 v[50:65], v[208:211], v[212:215], v[50:65]
	s_waitcnt lgkmcnt(5)
	v_mfma_f32_32x32x16_bf16 v[34:49], v[208:211], v[216:219], v[34:49]
	ds_read_b128 v[208:211], v147 offset:16384
	s_waitcnt lgkmcnt(5)
	v_mfma_f32_32x32x16_bf16 v[18:33], v[220:223], v[212:215], v[18:33]
	ds_read_b128 v[212:215], v151 offset:49152
	s_waitcnt lgkmcnt(6)
	v_mfma_f32_32x32x16_bf16 v[2:17], v[220:223], v[216:219], v[2:17]
	ds_read_b128 v[220:223], v151 offset:53248
	ds_read_b128 v[216:219], v147 offset:20480
	s_waitcnt lgkmcnt(6)
	v_mfma_f32_32x32x16_bf16 v[50:65], v[224:227], v[228:231], v[50:65]
	s_waitcnt lgkmcnt(5)
	v_mfma_f32_32x32x16_bf16 v[34:49], v[224:227], v[232:235], v[34:49]
	ds_read_b128 v[224:227], v148 offset:16384
	s_waitcnt lgkmcnt(5)
	v_mfma_f32_32x32x16_bf16 v[18:33], v[236:239], v[228:231], v[18:33]
	ds_read_b128 v[228:231], v152 offset:49152
	s_waitcnt lgkmcnt(6)
	v_mfma_f32_32x32x16_bf16 v[2:17], v[236:239], v[232:235], v[2:17]
	ds_read_b128 v[236:239], v152 offset:53248
	ds_read_b128 v[232:235], v148 offset:20480
	s_waitcnt lgkmcnt(6)
	v_mfma_f32_32x32x16_bf16 v[50:65], v[208:211], v[212:215], v[50:65]
	s_waitcnt lgkmcnt(5)
	v_mfma_f32_32x32x16_bf16 v[34:49], v[208:211], v[220:223], v[34:49]
	s_waitcnt lgkmcnt(4)
	v_mfma_f32_32x32x16_bf16 v[18:33], v[216:219], v[212:215], v[18:33]
	s_waitcnt lgkmcnt(4)
	v_mfma_f32_32x32x16_bf16 v[2:17], v[216:219], v[220:223], v[2:17]
	s_waitcnt lgkmcnt(2)
	v_mfma_f32_32x32x16_bf16 v[50:65], v[224:227], v[228:231], v[50:65]
	s_waitcnt lgkmcnt(1)
	v_mfma_f32_32x32x16_bf16 v[34:49], v[224:227], v[236:239], v[34:49]
	s_waitcnt lgkmcnt(0)
	v_mfma_f32_32x32x16_bf16 v[18:33], v[232:235], v[228:231], v[18:33]
	s_waitcnt lgkmcnt(0)
	v_mfma_f32_32x32x16_bf16 v[2:17], v[232:235], v[236:239], v[2:17]
	s_setprio 0
	s_andn2_b64 vcc, exec, s[88:89]
	s_cbranch_vccnz .LBB0_109
	ds_write_b128 v138, v[66:69]
	ds_write_b128 v138, v[70:73] offset:32768
	ds_write_b128 v138, v[74:77] offset:4096
	ds_write_b128 v138, v[78:81] offset:36864
	ds_write_b128 v138, v[86:89] offset:8192
	ds_write_b128 v138, v[94:97] offset:40960
	ds_write_b128 v138, v[102:105] offset:12288
	ds_write_b128 v138, v[126:129] offset:45056
	s_branch .LBB0_109

; #define GLOAD(RA, RB, kt_) _Pragma("unroll") for (int i = 0; i < 4; ++i) { \
;     RA[i] = *(const u32x4*)(Ap + (size_t)(32 * i) * lda + (kt_) * 64); \
;     RB[i] = *(const u32x4*)(Bp + (size_t)(32 * i) * ldb + (kt_) * 64); }
; #define LSTORE(RA, RB, buf_) _Pragma("unroll") for (int i = 0; i < 4; ++i) { \
;     *(u32x4*)(smem + (buf_) * 16384 + woff + i * 4096) = RA[i]; \
;     *(u32x4*)(smem + 32768 + (buf_) * 16384 + woff + i * 4096) = RB[i]; }
; DI void gemm_kloop(f32x16 (&acc)[2][2], const u16* __restrict__ A, int lda, const u16* __restrict__ B, int ldb, int K,
;                    char* smem) {
;     ...
;   const int woff = lr * 128 + ((lc ^ ((lr >> 1) & 7)) << 4);
;   const int sw = (r >> 1) & 7;
;   const int aoff = (wr * 64 + r) * 128, boff = 32768 + (wc * 64 + r) * 128;
;   GLOAD(ra0, rb0, 0)
;   GLOAD(ra1, rb1, 1)
;   __syncthreads();
;   LSTORE(ra0, rb0, 0)
;   __syncthreads();
; #pragma unroll 1
;   for (int kt = 0; kt < nk; kt += 2) {
;     if (kt + 2 < nk) GLOAD(ra0, rb0, kt + 2)
;     COMPUTE(0)
;     LSTORE(ra1, rb1, 1)
;     __syncthreads();
;     if (kt + 3 < nk) GLOAD(ra1, rb1, kt + 3)
;     COMPUTE(1)
;     if (kt + 2 < nk) LSTORE(ra0, rb0, 0)
;     __syncthreads();
; DI void gemm_merge_phase(const Params& p, int mrows, int bid, int nb, char* smem) {
;     ...
;     gemm_kloop(a, YRET + (size_t)row0 * 1024, 1024, WT + WT_A + (size_t)col0 * 1024, 1024, 1024, smem);
.LBB0_120:
	s_setprio 1
	v_add_u32_e32 v221, v216, v217
	v_add_u32_e32 v225, v215, v217
	v_add_u32_e32 v222, v216, v218
	v_add_u32_e32 v223, v216, v219
	v_add_u32_e32 v224, v216, v220
	v_add_u32_e32 v226, v215, v218
	v_add_u32_e32 v227, v215, v219
	v_add_u32_e32 v228, v215, v220
	ds_read_b128 v[230:233], v221
	ds_read_b128 v[234:237], v225 offset:32768
	ds_read_b128 v[238:241], v225 offset:36864
	ds_read_b128 v[248:251], v221 offset:4096
	ds_read_b128 v[252:255], v222
	s_waitcnt lgkmcnt(3)
	v_mfma_f32_32x32x16_bf16 v[50:65], v[230:233], v[234:237], v[50:65]
	s_waitcnt lgkmcnt(2)
	v_mfma_f32_32x32x16_bf16 v[34:49], v[230:233], v[238:241], v[34:49]
	ds_read_b128 v[230:233], v226 offset:32768
	s_waitcnt lgkmcnt(2)
	v_mfma_f32_32x32x16_bf16 v[18:33], v[248:251], v[234:237], v[18:33]
	ds_read_b128 v[234:237], v226 offset:36864
	s_waitcnt lgkmcnt(3)
	v_mfma_f32_32x32x16_bf16 v[2:17], v[248:251], v[238:241], v[2:17]
	ds_read_b128 v[248:251], v222 offset:4096
	ds_read_b128 v[238:241], v227 offset:32768
	s_waitcnt lgkmcnt(3)
	v_mfma_f32_32x32x16_bf16 v[50:65], v[252:255], v[230:233], v[50:65]
	s_waitcnt lgkmcnt(2)
	v_mfma_f32_32x32x16_bf16 v[34:49], v[252:255], v[234:237], v[34:49]
	ds_read_b128 v[252:255], v223
	s_waitcnt lgkmcnt(2)
	v_mfma_f32_32x32x16_bf16 v[18:33], v[248:251], v[230:233], v[18:33]
	ds_read_b128 v[230:233], v227 offset:36864
	s_waitcnt lgkmcnt(3)
	v_mfma_f32_32x32x16_bf16 v[2:17], v[248:251], v[234:237], v[2:17]
	ds_read_b128 v[248:251], v223 offset:4096
	ds_read_b128 v[234:237], v224
	s_waitcnt lgkmcnt(3)
	v_mfma_f32_32x32x16_bf16 v[50:65], v[252:255], v[238:241], v[50:65]
	s_waitcnt lgkmcnt(2)
	v_mfma_f32_32x32x16_bf16 v[34:49], v[252:255], v[230:233], v[34:49]
	ds_read_b128 v[252:255], v228 offset:32768
	s_waitcnt lgkmcnt(2)
	v_mfma_f32_32x32x16_bf16 v[18:33], v[248:251], v[238:241], v[18:33]
	ds_read_b128 v[238:241], v228 offset:36864
	s_waitcnt lgkmcnt(3)
	v_mfma_f32_32x32x16_bf16 v[2:17], v[248:251], v[230:233], v[2:17]
	ds_read_b128 v[248:251], v224 offset:4096
	s_waitcnt lgkmcnt(2)
	v_mfma_f32_32x32x16_bf16 v[50:65], v[234:237], v[252:255], v[50:65]
	s_waitcnt lgkmcnt(1)
	v_mfma_f32_32x32x16_bf16 v[34:49], v[234:237], v[238:241], v[34:49]
	s_waitcnt lgkmcnt(0)
	v_mfma_f32_32x32x16_bf16 v[18:33], v[248:251], v[252:255], v[18:33]
	s_waitcnt lgkmcnt(0)
	v_mfma_f32_32x32x16_bf16 v[2:17], v[248:251], v[238:241], v[2:17]
	s_setprio 0
	s_cmp_gt_u32 s9, 12
	s_waitcnt vmcnt(7)
	ds_write_b128 v214, v[94:97] offset:16384
	s_waitcnt vmcnt(6)
	ds_write_b128 v214, v[98:101] offset:49152
	s_waitcnt vmcnt(5)
	ds_write_b128 v214, v[102:105] offset:20480
	s_waitcnt vmcnt(4)
	ds_write_b128 v214, v[106:109] offset:53248
	s_waitcnt vmcnt(3)
	ds_write_b128 v214, v[114:117] offset:24576
	s_waitcnt vmcnt(2)
	ds_write_b128 v214, v[118:121] offset:57344
	s_waitcnt vmcnt(1)
	ds_write_b128 v214, v[122:125] offset:28672
	s_waitcnt vmcnt(0)
	ds_write_b128 v214, v[126:129] offset:61440
	s_waitcnt lgkmcnt(0)
	s_barrier
	s_cbranch_scc1 .LBB0_122
	v_add_co_u32_e32 v94, vcc, 0xfb60000, v136
	s_nop 1
	v_addc_co_u32_e32 v95, vcc, 0, v137, vcc
	v_add_co_u32_e32 v98, vcc, 0xdc0000, v134
	global_load_dwordx4 v[94:97], v[94:95], off offset:384
	s_nop 0
	v_addc_co_u32_e32 v99, vcc, 0, v135, vcc
	v_add_co_u32_e32 v102, vcc, 0xfb70000, v136
	global_load_dwordx4 v[98:101], v[98:99], off offset:384
	s_nop 0
	v_addc_co_u32_e32 v103, vcc, 0, v137, vcc
	v_add_co_u32_e32 v106, vcc, 0xdd0000, v134
	global_load_dwordx4 v[102:105], v[102:103], off offset:384
	s_nop 0
	v_addc_co_u32_e32 v107, vcc, 0, v135, vcc
	v_add_co_u32_e32 v114, vcc, 0xfb80000, v136
	global_load_dwordx4 v[106:109], v[106:107], off offset:384
	s_nop 0
	v_addc_co_u32_e32 v115, vcc, 0, v137, vcc
	v_add_co_u32_e32 v118, vcc, 0xde0000, v134
	global_load_dwordx4 v[114:117], v[114:115], off offset:384
	s_nop 0
	v_addc_co_u32_e32 v119, vcc, 0, v135, vcc
	v_add_co_u32_e32 v122, vcc, 0xfb90000, v136
	global_load_dwordx4 v[118:121], v[118:119], off offset:384
	s_nop 0
	v_addc_co_u32_e32 v123, vcc, 0, v137, vcc
	v_add_co_u32_e32 v126, vcc, 0xdf0000, v134
	global_load_dwordx4 v[122:125], v[122:123], off offset:384
	s_nop 0
	v_addc_co_u32_e32 v127, vcc, 0, v135, vcc
	global_load_dwordx4 v[126:129], v[126:127], off offset:384
.LBB0_122:
	s_setprio 1
	ds_read_b128 v[230:233], v221 offset:16384
	ds_read_b128 v[234:237], v225 offset:49152
	ds_read_b128 v[238:241], v225 offset:53248
	ds_read_b128 v[248:251], v221 offset:20480
	ds_read_b128 v[252:255], v222 offset:16384
	s_waitcnt lgkmcnt(3)
	v_mfma_f32_32x32x16_bf16 v[50:65], v[230:233], v[234:237], v[50:65]
	s_waitcnt lgkmcnt(2)
	v_mfma_f32_32x32x16_bf16 v[34:49], v[230:233], v[238:241], v[34:49]
	ds_read_b128 v[230:233], v226 offset:49152
	s_waitcnt lgkmcnt(2)
	v_mfma_f32_32x32x16_bf16 v[18:33], v[248:251], v[234:237], v[18:33]
	ds_read_b128 v[234:237], v226 offset:53248
	s_waitcnt lgkmcnt(3)
	v_mfma_f32_32x32x16_bf16 v[2:17], v[248:251], v[238:241], v[2:17]
	ds_read_b128 v[248:251], v222 offset:20480
	ds_read_b128 v[238:241], v223 offset:16384
	s_waitcnt lgkmcnt(3)
	v_mfma_f32_32x32x16_bf16 v[50:65], v[252:255], v[230:233], v[50:65]
	s_waitcnt lgkmcnt(2)
	v_mfma_f32_32x32x16_bf16 v[34:49], v[252:255], v[234:237], v[34:49]
	ds_read_b128 v[252:255], v227 offset:49152
	s_waitcnt lgkmcnt(2)
	v_mfma_f32_32x32x16_bf16 v[18:33], v[248:251], v[230:233], v[18:33]
	ds_read_b128 v[230:233], v227 offset:53248
	s_waitcnt lgkmcnt(3)
	v_mfma_f32_32x32x16_bf16 v[2:17], v[248:251], v[234:237], v[2:17]
	ds_read_b128 v[248:251], v223 offset:20480
	ds_read_b128 v[234:237], v224 offset:16384
	s_waitcnt lgkmcnt(3)
	v_mfma_f32_32x32x16_bf16 v[50:65], v[238:241], v[252:255], v[50:65]
	s_waitcnt lgkmcnt(2)
	v_mfma_f32_32x32x16_bf16 v[34:49], v[238:241], v[230:233], v[34:49]
	ds_read_b128 v[238:241], v228 offset:49152
	s_waitcnt lgkmcnt(2)
	v_mfma_f32_32x32x16_bf16 v[18:33], v[248:251], v[252:255], v[18:33]
	ds_read_b128 v[252:255], v228 offset:53248
	s_waitcnt lgkmcnt(3)
	v_mfma_f32_32x32x16_bf16 v[2:17], v[248:251], v[230:233], v[2:17]
	ds_read_b128 v[248:251], v224 offset:20480
	s_waitcnt lgkmcnt(2)
	v_mfma_f32_32x32x16_bf16 v[50:65], v[234:237], v[238:241], v[50:65]
	s_waitcnt lgkmcnt(1)
	v_mfma_f32_32x32x16_bf16 v[34:49], v[234:237], v[252:255], v[34:49]
	s_waitcnt lgkmcnt(0)
	v_mfma_f32_32x32x16_bf16 v[18:33], v[248:251], v[238:241], v[18:33]
	s_waitcnt lgkmcnt(0)
	v_mfma_f32_32x32x16_bf16 v[2:17], v[248:251], v[252:255], v[2:17]
	s_setprio 0
	s_andn2_b64 vcc, exec, s[88:89]
	s_cbranch_vccnz .LBB0_117
	ds_write_b128 v214, v[66:69]
	ds_write_b128 v214, v[70:73] offset:32768
	ds_write_b128 v214, v[74:77] offset:4096
	ds_write_b128 v214, v[78:81] offset:36864
	ds_write_b128 v214, v[82:85] offset:8192
	ds_write_b128 v214, v[86:89] offset:40960
	ds_write_b128 v214, v[90:93] offset:12288
	ds_write_b128 v214, v[110:113] offset:45056
	s_branch .LBB0_117

; #define GLOAD(RA, RB, kt_) _Pragma("unroll") for (int i = 0; i < 4; ++i) { \
;     RA[i] = *(const u32x4*)(Ap + (size_t)(32 * i) * lda + (kt_) * 64); \
;     RB[i] = *(const u32x4*)(Bp + (size_t)(32 * i) * ldb + (kt_) * 64); }
; #define LSTORE(RA, RB, buf_) _Pragma("unroll") for (int i = 0; i < 4; ++i) { \
;     *(u32x4*)(smem + (buf_) * 16384 + woff + i * 4096) = RA[i]; \
;     *(u32x4*)(smem + 32768 + (buf_) * 16384 + woff + i * 4096) = RB[i]; }
; DI void gemm_kloop(f32x16 (&acc)[2][2], const u16* __restrict__ A, int lda, const u16* __restrict__ B, int ldb, int K,
;                    char* smem) {
;     ...
;   const int woff = lr * 128 + ((lc ^ ((lr >> 1) & 7)) << 4);
;   const int sw = (r >> 1) & 7;
;   const int aoff = (wr * 64 + r) * 128, boff = 32768 + (wc * 64 + r) * 128;
;   GLOAD(ra0, rb0, 0)
;   GLOAD(ra1, rb1, 1)
;   __syncthreads();
;   LSTORE(ra0, rb0, 0)
;   __syncthreads();
; #pragma unroll 1
;   for (int kt = 0; kt < nk; kt += 2) {
;     if (kt + 2 < nk) GLOAD(ra0, rb0, kt + 2)
;     COMPUTE(0)
;     LSTORE(ra1, rb1, 1)
;     __syncthreads();
;     if (kt + 3 < nk) GLOAD(ra1, rb1, kt + 3)
;     COMPUTE(1)
;     if (kt + 2 < nk) LSTORE(ra0, rb0, 0)
;     __syncthreads();
; DI void gemm_merge_phase(const Params& p, int mrows, int bid, int nb, char* smem) {
;     ...
;     gemm_kloop(a, H + (size_t)row0 * 1024, 1024, WT + WT_IN + (size_t)(NIN + 1024 + col0) * 1024, 1024, 1024, smem);
.LBB0_128:
	s_setprio 1
	v_add_u32_e32 v145, v140, v141
	v_add_u32_e32 v149, v139, v141
	v_add_u32_e32 v146, v140, v142
	v_add_u32_e32 v147, v140, v143
	v_add_u32_e32 v148, v140, v144
	v_add_u32_e32 v150, v139, v142
	v_add_u32_e32 v151, v139, v143
	v_add_u32_e32 v152, v139, v144
	ds_read_b128 v[208:211], v145
	ds_read_b128 v[212:215], v149 offset:32768
	ds_read_b128 v[216:219], v149 offset:36864
	ds_read_b128 v[220:223], v145 offset:4096
	ds_read_b128 v[224:227], v146
	ds_read_b128 v[228:231], v150 offset:32768
	ds_read_b128 v[232:235], v150 offset:36864
	ds_read_b128 v[236:239], v146 offset:4096
	s_waitcnt lgkmcnt(6)
	v_mfma_f32_32x32x16_bf16 v[50:65], v[208:211], v[212:215], v[50:65]
	s_waitcnt lgkmcnt(5)
	v_mfma_f32_32x32x16_bf16 v[34:49], v[208:211], v[216:219], v[34:49]
	ds_read_b128 v[208:211], v151 offset:32768
	s_waitcnt lgkmcnt(5)
	v_mfma_f32_32x32x16_bf16 v[18:33], v[220:223], v[212:215], v[18:33]
	ds_read_b128 v[212:215], v147
	s_waitcnt lgkmcnt(6)
	v_mfma_f32_32x32x16_bf16 v[2:17], v[220:223], v[216:219], v[2:17]
	ds_read_b128 v[220:223], v151 offset:36864
	ds_read_b128 v[216:219], v147 offset:4096
	s_waitcnt lgkmcnt(6)
	v_mfma_f32_32x32x16_bf16 v[50:65], v[224:227], v[228:231], v[50:65]
	s_waitcnt lgkmcnt(5)
	v_mfma_f32_32x32x16_bf16 v[34:49], v[224:227], v[232:235], v[34:49]
	ds_read_b128 v[224:227], v148
	s_waitcnt lgkmcnt(5)
	v_mfma_f32_32x32x16_bf16 v[18:33], v[236:239], v[228:231], v[18:33]
	ds_read_b128 v[228:231], v152 offset:32768
	s_waitcnt lgkmcnt(6)
	v_mfma_f32_32x32x16_bf16 v[2:17], v[236:239], v[232:235], v[2:17]
	ds_read_b128 v[236:239], v152 offset:36864
	ds_read_b128 v[232:235], v148 offset:4096
	s_waitcnt lgkmcnt(6)
	v_mfma_f32_32x32x16_bf16 v[50:65], v[212:215], v[208:211], v[50:65]
	s_waitcnt lgkmcnt(5)
	v_mfma_f32_32x32x16_bf16 v[34:49], v[212:215], v[220:223], v[34:49]
	s_waitcnt lgkmcnt(4)
	v_mfma_f32_32x32x16_bf16 v[18:33], v[216:219], v[208:211], v[18:33]
	s_waitcnt lgkmcnt(4)
	v_mfma_f32_32x32x16_bf16 v[2:17], v[216:219], v[220:223], v[2:17]
	s_waitcnt lgkmcnt(2)
	v_mfma_f32_32x32x16_bf16 v[50:65], v[224:227], v[228:231], v[50:65]
	s_waitcnt lgkmcnt(1)
	v_mfma_f32_32x32x16_bf16 v[34:49], v[224:227], v[236:239], v[34:49]
	s_waitcnt lgkmcnt(0)
	v_mfma_f32_32x32x16_bf16 v[18:33], v[232:235], v[228:231], v[18:33]
	s_waitcnt lgkmcnt(0)
	v_mfma_f32_32x32x16_bf16 v[2:17], v[232:235], v[236:239], v[2:17]
	s_setprio 0
	s_cmp_gt_u32 s9, 12
	s_waitcnt vmcnt(7)
	ds_write_b128 v138, v[82:85] offset:16384
	s_waitcnt vmcnt(6)
	ds_write_b128 v138, v[86:89] offset:49152
	s_waitcnt vmcnt(5)
	ds_write_b128 v138, v[94:97] offset:20480
	s_waitcnt vmcnt(4)
	ds_write_b128 v138, v[102:105] offset:53248
	s_waitcnt vmcnt(3)
	ds_write_b128 v138, v[106:109] offset:24576
	s_waitcnt vmcnt(2)
	ds_write_b128 v138, v[114:117] offset:57344
	s_waitcnt vmcnt(1)
	ds_write_b128 v138, v[118:121] offset:28672
	s_waitcnt vmcnt(0)
	ds_write_b128 v138, v[122:125] offset:61440
	s_waitcnt lgkmcnt(0)
	s_barrier
	s_cbranch_scc1 .LBB0_130
	v_add_co_u32_e32 v82, vcc, 0x2360000, v136
	s_nop 1
	v_addc_co_u32_e32 v83, vcc, 0, v137, vcc
	v_add_co_u32_e32 v86, vcc, 0xbc0000, v134
	global_load_dwordx4 v[82:85], v[82:83], off offset:384
	s_nop 0
	v_addc_co_u32_e32 v87, vcc, 0, v135, vcc
	v_add_co_u32_e32 v94, vcc, 0x2370000, v136
	global_load_dwordx4 v[86:89], v[86:87], off offset:384
	s_nop 0
	v_addc_co_u32_e32 v95, vcc, 0, v137, vcc
	v_add_co_u32_e32 v102, vcc, 0xbd0000, v134
	global_load_dwordx4 v[94:97], v[94:95], off offset:384
	s_nop 0
	v_addc_co_u32_e32 v103, vcc, 0, v135, vcc
	v_add_co_u32_e32 v106, vcc, 0x2380000, v136
	global_load_dwordx4 v[102:105], v[102:103], off offset:384
	s_nop 0
	v_addc_co_u32_e32 v107, vcc, 0, v137, vcc
	v_add_co_u32_e32 v114, vcc, 0xbe0000, v134
	global_load_dwordx4 v[106:109], v[106:107], off offset:384
	s_nop 0
	v_addc_co_u32_e32 v115, vcc, 0, v135, vcc
	v_add_co_u32_e32 v118, vcc, 0x2390000, v136
	global_load_dwordx4 v[114:117], v[114:115], off offset:384
	s_nop 0
	v_addc_co_u32_e32 v119, vcc, 0, v137, vcc
	v_add_co_u32_e32 v122, vcc, 0xbf0000, v134
	global_load_dwordx4 v[118:121], v[118:119], off offset:384
	s_nop 0
	v_addc_co_u32_e32 v123, vcc, 0, v135, vcc
	global_load_dwordx4 v[122:125], v[122:123], off offset:384
.LBB0_130:
	s_setprio 1
	ds_read_b128 v[208:211], v145 offset:16384
	ds_read_b128 v[212:215], v149 offset:49152
	ds_read_b128 v[216:219], v149 offset:53248
	ds_read_b128 v[220:223], v145 offset:20480
	ds_read_b128 v[224:227], v146 offset:16384
	ds_read_b128 v[228:231], v150 offset:49152
	ds_read_b128 v[232:235], v150 offset:53248
	ds_read_b128 v[236:239], v146 offset:20480
	s_waitcnt lgkmcnt(6)
	v_mfma_f32_32x32x16_bf16 v[50:65], v[208:211], v[212:215], v[50:65]
	s_waitcnt lgkmcnt(5)
	v_mfma_f32_32x32x16_bf16 v[34:49], v[208:211], v[216:219], v[34:49]
	ds_read_b128 v[208:211], v147 offset:16384
	s_waitcnt lgkmcnt(5)
	v_mfma_f32_32x32x16_bf16 v[18:33], v[220:223], v[212:215], v[18:33]
	ds_read_b128 v[212:215], v151 offset:49152
	s_waitcnt lgkmcnt(6)
	v_mfma_f32_32x32x16_bf16 v[2:17], v[220:223], v[216:219], v[2:17]
	ds_read_b128 v[220:223], v151 offset:53248
	ds_read_b128 v[216:219], v147 offset:20480
	s_waitcnt lgkmcnt(6)
	v_mfma_f32_32x32x16_bf16 v[50:65], v[224:227], v[228:231], v[50:65]
	s_waitcnt lgkmcnt(5)
	v_mfma_f32_32x32x16_bf16 v[34:49], v[224:227], v[232:235], v[34:49]
	ds_read_b128 v[224:227], v148 offset:16384
	s_waitcnt lgkmcnt(5)
	v_mfma_f32_32x32x16_bf16 v[18:33], v[236:239], v[228:231], v[18:33]
	ds_read_b128 v[228:231], v152 offset:49152
	s_waitcnt lgkmcnt(6)
	v_mfma_f32_32x32x16_bf16 v[2:17], v[236:239], v[232:235], v[2:17]
	ds_read_b128 v[236:239], v152 offset:53248
	ds_read_b128 v[232:235], v148 offset:20480
	s_waitcnt lgkmcnt(6)
	v_mfma_f32_32x32x16_bf16 v[50:65], v[208:211], v[212:215], v[50:65]
	s_waitcnt lgkmcnt(5)
	v_mfma_f32_32x32x16_bf16 v[34:49], v[208:211], v[220:223], v[34:49]
	s_waitcnt lgkmcnt(4)
	v_mfma_f32_32x32x16_bf16 v[18:33], v[216:219], v[212:215], v[18:33]
	s_waitcnt lgkmcnt(4)
	v_mfma_f32_32x32x16_bf16 v[2:17], v[216:219], v[220:223], v[2:17]
	s_waitcnt lgkmcnt(2)
	v_mfma_f32_32x32x16_bf16 v[50:65], v[224:227], v[228:231], v[50:65]
	s_waitcnt lgkmcnt(1)
	v_mfma_f32_32x32x16_bf16 v[34:49], v[224:227], v[236:239], v[34:49]
	s_waitcnt lgkmcnt(0)
	v_mfma_f32_32x32x16_bf16 v[18:33], v[232:235], v[228:231], v[18:33]
	s_waitcnt lgkmcnt(0)
	v_mfma_f32_32x32x16_bf16 v[2:17], v[232:235], v[236:239], v[2:17]
	s_setprio 0
	s_andn2_b64 vcc, exec, s[44:45]
	s_cbranch_vccnz .LBB0_125
	ds_write_b128 v138, v[66:69]
	ds_write_b128 v138, v[70:73] offset:32768
	ds_write_b128 v138, v[74:77] offset:4096
	ds_write_b128 v138, v[78:81] offset:36864
	ds_write_b128 v138, v[90:93] offset:8192
	ds_write_b128 v138, v[98:101] offset:40960
	ds_write_b128 v138, v[110:113] offset:12288
	ds_write_b128 v138, v[126:129] offset:45056
	s_branch .LBB0_125

; #define GLOAD(RA, RB, kt_) _Pragma("unroll") for (int i = 0; i < 4; ++i) { \
;     RA[i] = *(const u32x4*)(Ap + (size_t)(32 * i) * lda + (kt_) * 64); \
;     RB[i] = *(const u32x4*)(Bp + (size_t)(32 * i) * ldb + (kt_) * 64); }
; #define LSTORE(RA, RB, buf_) _Pragma("unroll") for (int i = 0; i < 4; ++i) { \
;     *(u32x4*)(smem + (buf_) * 16384 + woff + i * 4096) = RA[i]; \
;     *(u32x4*)(smem + 32768 + (buf_) * 16384 + woff + i * 4096) = RB[i]; }
; DI void gemm_kloop(f32x16 (&acc)[2][2], const u16* __restrict__ A, int lda, const u16* __restrict__ B, int ldb, int K,
;                    char* smem) {
;     ...
;   const int woff = lr * 128 + ((lc ^ ((lr >> 1) & 7)) << 4);
;   const int sw = (r >> 1) & 7;
;   const int aoff = (wr * 64 + r) * 128, boff = 32768 + (wc * 64 + r) * 128;
;   GLOAD(ra0, rb0, 0)
;   GLOAD(ra1, rb1, 1)
;   __syncthreads();
;   LSTORE(ra0, rb0, 0)
;   __syncthreads();
; #pragma unroll 1
;   for (int kt = 0; kt < nk; kt += 2) {
;     if (kt + 2 < nk) GLOAD(ra0, rb0, kt + 2)
;     COMPUTE(0)
;     LSTORE(ra1, rb1, 1)
;     __syncthreads();
;     if (kt + 3 < nk) GLOAD(ra1, rb1, kt + 3)
;     COMPUTE(1)
;     if (kt + 2 < nk) LSTORE(ra0, rb0, 0)
;     __syncthreads();
; DI void gemm_merge_phase(const Params& p, int mrows, int bid, int nb, char* smem) {
;     ...
;     gemm_kloop(a, YRW + (size_t)row0 * 512, 512, WT + WT_B + (size_t)col0 * 512, 512, 512, smem);
.LBB0_136:
	s_setprio 1
	v_add_u32_e32 v221, v216, v217
	v_add_u32_e32 v225, v215, v217
	v_add_u32_e32 v222, v216, v218
	v_add_u32_e32 v223, v216, v219
	v_add_u32_e32 v224, v216, v220
	v_add_u32_e32 v226, v215, v218
	v_add_u32_e32 v227, v215, v219
	v_add_u32_e32 v228, v215, v220
	ds_read_b128 v[230:233], v221
	ds_read_b128 v[234:237], v225 offset:32768
	ds_read_b128 v[238:241], v225 offset:36864
	ds_read_b128 v[248:251], v221 offset:4096
	ds_read_b128 v[252:255], v222
	s_waitcnt lgkmcnt(3)
	v_mfma_f32_32x32x16_bf16 v[50:65], v[230:233], v[234:237], v[50:65]
	s_waitcnt lgkmcnt(2)
	v_mfma_f32_32x32x16_bf16 v[34:49], v[230:233], v[238:241], v[34:49]
	ds_read_b128 v[230:233], v226 offset:32768
	s_waitcnt lgkmcnt(2)
	v_mfma_f32_32x32x16_bf16 v[18:33], v[248:251], v[234:237], v[18:33]
	ds_read_b128 v[234:237], v226 offset:36864
	s_waitcnt lgkmcnt(3)
	v_mfma_f32_32x32x16_bf16 v[2:17], v[248:251], v[238:241], v[2:17]
	ds_read_b128 v[248:251], v222 offset:4096
	ds_read_b128 v[238:241], v227 offset:32768
	s_waitcnt lgkmcnt(3)
	v_mfma_f32_32x32x16_bf16 v[50:65], v[252:255], v[230:233], v[50:65]
	s_waitcnt lgkmcnt(2)
	v_mfma_f32_32x32x16_bf16 v[34:49], v[252:255], v[234:237], v[34:49]
	ds_read_b128 v[252:255], v223
	s_waitcnt lgkmcnt(2)
	v_mfma_f32_32x32x16_bf16 v[18:33], v[248:251], v[230:233], v[18:33]
	ds_read_b128 v[230:233], v227 offset:36864
	s_waitcnt lgkmcnt(3)
	v_mfma_f32_32x32x16_bf16 v[2:17], v[248:251], v[234:237], v[2:17]
	ds_read_b128 v[248:251], v223 offset:4096
	ds_read_b128 v[234:237], v224
	s_waitcnt lgkmcnt(3)
	v_mfma_f32_32x32x16_bf16 v[50:65], v[252:255], v[238:241], v[50:65]
	s_waitcnt lgkmcnt(2)
	v_mfma_f32_32x32x16_bf16 v[34:49], v[252:255], v[230:233], v[34:49]
	ds_read_b128 v[252:255], v228 offset:32768
	s_waitcnt lgkmcnt(2)
	v_mfma_f32_32x32x16_bf16 v[18:33], v[248:251], v[238:241], v[18:33]
	ds_read_b128 v[238:241], v228 offset:36864
	s_waitcnt lgkmcnt(3)
	v_mfma_f32_32x32x16_bf16 v[2:17], v[248:251], v[230:233], v[2:17]
	ds_read_b128 v[248:251], v224 offset:4096
	s_waitcnt lgkmcnt(2)
	v_mfma_f32_32x32x16_bf16 v[50:65], v[234:237], v[252:255], v[50:65]
	s_waitcnt lgkmcnt(1)
	v_mfma_f32_32x32x16_bf16 v[34:49], v[234:237], v[238:241], v[34:49]
	s_waitcnt lgkmcnt(0)
	v_mfma_f32_32x32x16_bf16 v[18:33], v[248:251], v[252:255], v[18:33]
	s_waitcnt lgkmcnt(0)
	v_mfma_f32_32x32x16_bf16 v[2:17], v[248:251], v[238:241], v[2:17]
	s_setprio 0
	s_cmp_gt_u32 s7, 4
	s_waitcnt vmcnt(7)
	ds_write_b128 v214, v[94:97] offset:16384
	s_waitcnt vmcnt(6)
	ds_write_b128 v214, v[98:101] offset:49152
	s_waitcnt vmcnt(5)
	ds_write_b128 v214, v[102:105] offset:20480
	s_waitcnt vmcnt(4)
	ds_write_b128 v214, v[106:109] offset:53248
	s_waitcnt vmcnt(3)
	ds_write_b128 v214, v[114:117] offset:24576
	s_waitcnt vmcnt(2)
	ds_write_b128 v214, v[118:121] offset:57344
	s_waitcnt vmcnt(1)
	ds_write_b128 v214, v[122:125] offset:28672
	s_waitcnt vmcnt(0)
	ds_write_b128 v214, v[126:129] offset:61440
	s_waitcnt lgkmcnt(0)
	s_barrier
	s_cbranch_scc1 .LBB0_138
	v_add_co_u32_e32 v94, vcc, 0xb360000, v136
	s_nop 1
	v_addc_co_u32_e32 v95, vcc, 0, v137, vcc
	v_add_co_u32_e32 v98, vcc, 0xfc0000, v134
	global_load_dwordx4 v[94:97], v[94:95], off offset:384
	s_nop 0
	v_addc_co_u32_e32 v99, vcc, 0, v135, vcc
	v_add_co_u32_e32 v102, vcc, 0xb368000, v136
	global_load_dwordx4 v[98:101], v[98:99], off offset:384
	s_nop 0
	v_addc_co_u32_e32 v103, vcc, 0, v137, vcc
	v_add_co_u32_e32 v106, vcc, 0xfc8000, v134
	global_load_dwordx4 v[102:105], v[102:103], off offset:384
	s_nop 0
	v_addc_co_u32_e32 v107, vcc, 0, v135, vcc
	v_add_co_u32_e32 v114, vcc, 0xb370000, v136
	global_load_dwordx4 v[106:109], v[106:107], off offset:384
	s_nop 0
	v_addc_co_u32_e32 v115, vcc, 0, v137, vcc
	v_add_co_u32_e32 v118, vcc, 0xfd0000, v134
	global_load_dwordx4 v[114:117], v[114:115], off offset:384
	s_nop 0
	v_addc_co_u32_e32 v119, vcc, 0, v135, vcc
	v_add_co_u32_e32 v122, vcc, 0xb378000, v136
	global_load_dwordx4 v[118:121], v[118:119], off offset:384
	s_nop 0
	v_addc_co_u32_e32 v123, vcc, 0, v137, vcc
	v_add_co_u32_e32 v126, vcc, 0xfd8000, v134
	global_load_dwordx4 v[122:125], v[122:123], off offset:384
	s_nop 0
	v_addc_co_u32_e32 v127, vcc, 0, v135, vcc
	global_load_dwordx4 v[126:129], v[126:127], off offset:384
.LBB0_138:
	s_setprio 1
	ds_read_b128 v[230:233], v221 offset:16384
	ds_read_b128 v[234:237], v225 offset:49152
	ds_read_b128 v[238:241], v225 offset:53248
	ds_read_b128 v[248:251], v221 offset:20480
	ds_read_b128 v[252:255], v222 offset:16384
	s_waitcnt lgkmcnt(3)
	v_mfma_f32_32x32x16_bf16 v[50:65], v[230:233], v[234:237], v[50:65]
	s_waitcnt lgkmcnt(2)
	v_mfma_f32_32x32x16_bf16 v[34:49], v[230:233], v[238:241], v[34:49]
	ds_read_b128 v[230:233], v226 offset:49152
	s_waitcnt lgkmcnt(2)
	v_mfma_f32_32x32x16_bf16 v[18:33], v[248:251], v[234:237], v[18:33]
	ds_read_b128 v[234:237], v226 offset:53248
	s_waitcnt lgkmcnt(3)
	v_mfma_f32_32x32x16_bf16 v[2:17], v[248:251], v[238:241], v[2:17]
	ds_read_b128 v[248:251], v222 offset:20480
	ds_read_b128 v[238:241], v223 offset:16384
	s_waitcnt lgkmcnt(3)
	v_mfma_f32_32x32x16_bf16 v[50:65], v[252:255], v[230:233], v[50:65]
	s_waitcnt lgkmcnt(2)
	v_mfma_f32_32x32x16_bf16 v[34:49], v[252:255], v[234:237], v[34:49]
	ds_read_b128 v[252:255], v227 offset:49152
	s_waitcnt lgkmcnt(2)
	v_mfma_f32_32x32x16_bf16 v[18:33], v[248:251], v[230:233], v[18:33]
	ds_read_b128 v[230:233], v227 offset:53248
	s_waitcnt lgkmcnt(3)
	v_mfma_f32_32x32x16_bf16 v[2:17], v[248:251], v[234:237], v[2:17]
	ds_read_b128 v[248:251], v223 offset:20480
	ds_read_b128 v[234:237], v224 offset:16384
	s_waitcnt lgkmcnt(3)
	v_mfma_f32_32x32x16_bf16 v[50:65], v[238:241], v[252:255], v[50:65]
	s_waitcnt lgkmcnt(2)
	v_mfma_f32_32x32x16_bf16 v[34:49], v[238:241], v[230:233], v[34:49]
	ds_read_b128 v[238:241], v228 offset:49152
	s_waitcnt lgkmcnt(2)
	v_mfma_f32_32x32x16_bf16 v[18:33], v[248:251], v[252:255], v[18:33]
	ds_read_b128 v[252:255], v228 offset:53248
	s_waitcnt lgkmcnt(3)
	v_mfma_f32_32x32x16_bf16 v[2:17], v[248:251], v[230:233], v[2:17]
	ds_read_b128 v[248:251], v224 offset:20480
	s_waitcnt lgkmcnt(2)
	v_mfma_f32_32x32x16_bf16 v[50:65], v[234:237], v[238:241], v[50:65]
	s_waitcnt lgkmcnt(1)
	v_mfma_f32_32x32x16_bf16 v[34:49], v[234:237], v[252:255], v[34:49]
	s_waitcnt lgkmcnt(0)
	v_mfma_f32_32x32x16_bf16 v[18:33], v[248:251], v[238:241], v[18:33]
	s_waitcnt lgkmcnt(0)
	v_mfma_f32_32x32x16_bf16 v[2:17], v[248:251], v[252:255], v[2:17]
	s_setprio 0
	s_andn2_b64 vcc, exec, s[40:41]
	s_cbranch_vccnz .LBB0_133
	ds_write_b128 v214, v[66:69]
	ds_write_b128 v214, v[70:73] offset:32768
	ds_write_b128 v214, v[74:77] offset:4096
	ds_write_b128 v214, v[78:81] offset:36864
	ds_write_b128 v214, v[82:85] offset:8192
	ds_write_b128 v214, v[86:89] offset:40960
	ds_write_b128 v214, v[90:93] offset:12288
	ds_write_b128 v214, v[110:113] offset:45056
	s_branch .LBB0_133
